# silu(z_attn) epilogue loads of each attention item issued at the top of its last step
# baseline (speedup 1.0000x reference)
; #define LAS __attribute__((address_space(3)))
; __device__ __forceinline__ void phase_attn(const Params& p, LAS unsigned char* lds, unsigned* queue) {
;     ...
;         for (int n = 0; n < ntile; n += 2) {
;             if (n + 2 < ntile) {
; #pragma unroll
;                 for (int q = 0; q < 2; ++q) { const int m = n + 2 + q; const int kp = m < 4 ? blk * 256 + 64 * m : ((m - 4) >> 2) * 256 + 64 * ((m - 4) & 3);
;                     kreg[q] = *(const u32x4*)(Kst + (size_t)kp * 64); vreg[q] = *(const u32x4*)(Vst + kp); }
;             }
;             LAS unsigned char* SB = lds + ((n >> 1) & 1) * (2 * BUFB);
;             if (n >= 4) {
;                 const bool on = (selmask >> ((n - 4) >> 2)) & 1u;
;                 if (__ballot(on) != 0ull) attn_tile2(SB, SB + BUFB, kf_off, vf_off, qf, O0, O1, mrun, lrun, on);
;             } else {
; #pragma unroll
;                 for (int q = 0; q < 2; ++q) {
;                     const int nn = n + q;
;                     const int kpos0 = blk * 256 + 64 * nn;
;                     LAS unsigned char* B = SB + q * BUFB;
;                     const int dt_ = w >> 1;
;                     if (nn == dt_) attn_tile<true>(B, kf_off, vf_off, qf, O0, O1, mrun, lrun, true, kpos0, qpos, hh);
;                     else if (nn < dt_) attn_tile<false>(B, kf_off, vf_off, qf, O0, O1, mrun, lrun, true, kpos0, qpos, hh);
;                 }
;             }
;             if (n + 2 < ntile) { LAS unsigned char* Bn = lds + (((n >> 1) + 1) & 1) * (2 * BUFB);
; #pragma unroll
;                 for (int q = 0; q < 2; ++q) { *(LAS u32x4*)(Bn + q * BUFB + st_off) = kreg[q]; *(LAS u32x4*)(Bn + q * BUFB + TILEB + st_off) = vreg[q]; } }
;             __syncthreads();
;         }
.LBB0_395:
	s_nop 9
	v_mov_b64_e32 v[96:97], v[48:49]
	v_mov_b64_e32 v[112:113], v[32:33]
	v_mov_b32_e32 v4, v2
	v_mov_b32_e32 v5, v214
	v_mov_b64_e32 v[94:95], v[46:47]
	v_mov_b64_e32 v[92:93], v[44:45]
	v_mov_b64_e32 v[90:91], v[42:43]
	v_mov_b64_e32 v[88:89], v[40:41]
	v_mov_b64_e32 v[86:87], v[38:39]
	v_mov_b64_e32 v[84:85], v[36:37]
	v_mov_b64_e32 v[82:83], v[34:35]
	v_mov_b64_e32 v[110:111], v[30:31]
	v_mov_b64_e32 v[108:109], v[28:29]
	v_mov_b64_e32 v[106:107], v[26:27]
	v_mov_b64_e32 v[104:105], v[24:25]
	v_mov_b64_e32 v[102:103], v[22:23]
	v_mov_b64_e32 v[100:101], v[20:21]
	v_mov_b64_e32 v[98:99], v[18:19]
	s_andn2_b64 vcc, exec, s[86:87]
	s_cbranch_vccz .LBB0_417
	s_branch .LBB0_418
